# prompt MLA epilogue: permlane32_swap pairs, 16x dwordx2 stores widened to 8x dwordx4 per wave
# speedup vs baseline: 1.0010x; 1.0010x over previous
; DI unsigned pk2(float lo, float hi) { fv2 v = {lo, hi}; return __builtin_bit_cast(unsigned, __builtin_convertvector(v, bfv2)); }
; DI float rcpf(float x) { return __builtin_amdgcn_rcpf(x); }
; DI int lane_id() { int l; asm volatile("v_mbcnt_lo_u32_b32 %0, -1, 0\n\tv_mbcnt_hi_u32_b32 %0, -1, %0" : "=v"(l)); return l; }
; template <int DQK, bool MLA, bool QREG = true>
; DI void attn_unit(LAS unsigned char* lds, const bf16_t* Q, int ldq, int nqv, const bf16_t* K1, int ldk1, const bf16_t* K2, const bf16_t* VT, int ldv,
;                   int ntiles, int lim, int nkeys, bf16_t* O, int ldo, int tid, int wid, int lane) {
;     ...
;     lrun += __shfl_xor(lrun, 32);
;     const float il = rcpf(lrun);
;     const int t3 = lane_id();
;     const int qrow = wid * 32 + (t3 & 31), h3 = t3 >> 5;
;     if (lim > 0 && qrow < nqv) {
;         bf16_t* op = O + (size_t)qrow * ldo + 4 * h3;
; #pragma unroll
;         for (int v4 = 0; v4 < 4; ++v4)
; #pragma unroll
;             for (int g4 = 0; g4 < 4; ++g4) {
;                 u32x2 w; w.x = pk2(o[v4][4 * g4] * il, o[v4][4 * g4 + 1] * il); w.y = pk2(o[v4][4 * g4 + 2] * il, o[v4][4 * g4 + 3] * il);
;                 *(u32x2*)(op + 32 * v4 + 8 * g4) = w;
;             }
;     }
.LBB0_1325:
	v_cmp_lt_i32_e32 vcc, v5, v6
	s_barrier
	s_nop 0
	v_cndmask_b32_e32 v0, v4, v5, vcc
	v_lshlrev_b32_e32 v0, 2, v0
	ds_bpermute_b32 v0, v0, v183
	s_and_b64 vcc, exec, s[84:85]
	s_waitcnt lgkmcnt(0)
	v_mbcnt_lo_u32_b32 v2, -1, 0
	v_mbcnt_hi_u32_b32 v2, -1, v2
	s_cbranch_vccz .LBB0_1285
	s_lshl_b64 s[14:15], s[14:15], 11
	v_add_f32_e32 v0, v183, v0
	s_add_u32 s14, s27, s14
	v_rcp_f32_e32 v4, v0
	v_and_or_b32 v0, v2, 31, s86
	s_addc_u32 s15, s28, s15
	v_lshlrev_b32_e32 v0, 11, v0
	v_lshl_add_u64 v[6:7], s[14:15], 0, v[0:1]
	v_ashrrev_i32_e32 v0, 3, v2
	v_and_b32_e32 v2, -4, v0
	v_lshlrev_b32_e32 v2, 1, v2
	v_ashrrev_i32_e32 v3, 31, v2
	v_lshl_add_u64 v[2:3], v[2:3], 1, v[6:7]
	v_pk_mul_f32 v[8:9], v[64:65], v[4:5] op_sel_hi:[1,0]
	v_pk_mul_f32 v[10:11], v[66:67], v[4:5] op_sel_hi:[1,0]
	v_pk_mul_f32 v[12:13], v[68:69], v[4:5] op_sel_hi:[1,0]
	v_pk_mul_f32 v[14:15], v[70:71], v[4:5] op_sel_hi:[1,0]
	v_cvt_pk_bf16_f32 v8, v8, v9
	v_cvt_pk_bf16_f32 v9, v10, v11
	v_cvt_pk_bf16_f32 v10, v12, v13
	v_cvt_pk_bf16_f32 v11, v14, v15
	s_nop 1
	v_permlane32_swap_b32 v8, v10
	v_permlane32_swap_b32 v9, v11
	global_store_dwordx4 v[2:3], v[8:11], off
	s_nop 1
	v_pk_mul_f32 v[8:9], v[72:73], v[4:5] op_sel_hi:[1,0]
	v_pk_mul_f32 v[10:11], v[74:75], v[4:5] op_sel_hi:[1,0]
	v_pk_mul_f32 v[12:13], v[76:77], v[4:5] op_sel_hi:[1,0]
	v_pk_mul_f32 v[14:15], v[78:79], v[4:5] op_sel_hi:[1,0]
	v_cvt_pk_bf16_f32 v8, v8, v9
	v_cvt_pk_bf16_f32 v9, v10, v11
	v_cvt_pk_bf16_f32 v10, v12, v13
	v_cvt_pk_bf16_f32 v11, v14, v15
	s_nop 1
	v_permlane32_swap_b32 v8, v10
	v_permlane32_swap_b32 v9, v11
	global_store_dwordx4 v[2:3], v[8:11], off offset:32
	s_nop 1
	v_pk_mul_f32 v[8:9], v[48:49], v[4:5] op_sel_hi:[1,0]
	v_pk_mul_f32 v[10:11], v[50:51], v[4:5] op_sel_hi:[1,0]
	v_pk_mul_f32 v[12:13], v[52:53], v[4:5] op_sel_hi:[1,0]
	v_pk_mul_f32 v[14:15], v[54:55], v[4:5] op_sel_hi:[1,0]
	v_cvt_pk_bf16_f32 v8, v8, v9
	v_cvt_pk_bf16_f32 v9, v10, v11
	v_cvt_pk_bf16_f32 v10, v12, v13
	v_cvt_pk_bf16_f32 v11, v14, v15
	s_nop 1
	v_permlane32_swap_b32 v8, v10
	v_permlane32_swap_b32 v9, v11
	global_store_dwordx4 v[2:3], v[8:11], off offset:64
	s_nop 1
	v_pk_mul_f32 v[8:9], v[56:57], v[4:5] op_sel_hi:[1,0]
	v_pk_mul_f32 v[10:11], v[58:59], v[4:5] op_sel_hi:[1,0]
	v_pk_mul_f32 v[12:13], v[60:61], v[4:5] op_sel_hi:[1,0]
	v_pk_mul_f32 v[14:15], v[62:63], v[4:5] op_sel_hi:[1,0]
	v_cvt_pk_bf16_f32 v8, v8, v9
	v_cvt_pk_bf16_f32 v9, v10, v11
	v_cvt_pk_bf16_f32 v10, v12, v13
	v_cvt_pk_bf16_f32 v11, v14, v15
	s_nop 1
	v_permlane32_swap_b32 v8, v10
	v_permlane32_swap_b32 v9, v11
	global_store_dwordx4 v[2:3], v[8:11], off offset:96
	s_nop 1
	v_pk_mul_f32 v[8:9], v[32:33], v[4:5] op_sel_hi:[1,0]
	v_pk_mul_f32 v[10:11], v[34:35], v[4:5] op_sel_hi:[1,0]
	v_pk_mul_f32 v[12:13], v[36:37], v[4:5] op_sel_hi:[1,0]
	v_pk_mul_f32 v[14:15], v[38:39], v[4:5] op_sel_hi:[1,0]
	v_cvt_pk_bf16_f32 v8, v8, v9
	v_cvt_pk_bf16_f32 v9, v10, v11
	v_cvt_pk_bf16_f32 v10, v12, v13
	v_cvt_pk_bf16_f32 v11, v14, v15
	s_nop 1
	v_permlane32_swap_b32 v8, v10
	v_permlane32_swap_b32 v9, v11
	global_store_dwordx4 v[2:3], v[8:11], off offset:128
	s_nop 1
	v_pk_mul_f32 v[8:9], v[40:41], v[4:5] op_sel_hi:[1,0]
	v_pk_mul_f32 v[10:11], v[42:43], v[4:5] op_sel_hi:[1,0]
	v_pk_mul_f32 v[12:13], v[44:45], v[4:5] op_sel_hi:[1,0]
	v_pk_mul_f32 v[14:15], v[46:47], v[4:5] op_sel_hi:[1,0]
	v_cvt_pk_bf16_f32 v8, v8, v9
	v_cvt_pk_bf16_f32 v9, v10, v11
	v_cvt_pk_bf16_f32 v10, v12, v13
	v_cvt_pk_bf16_f32 v11, v14, v15
	s_nop 1
	v_permlane32_swap_b32 v8, v10
	v_permlane32_swap_b32 v9, v11
	global_store_dwordx4 v[2:3], v[8:11], off offset:160
	s_nop 1
	v_pk_mul_f32 v[8:9], v[16:17], v[4:5] op_sel_hi:[1,0]
	v_pk_mul_f32 v[10:11], v[18:19], v[4:5] op_sel_hi:[1,0]
	v_pk_mul_f32 v[12:13], v[20:21], v[4:5] op_sel_hi:[1,0]
	v_pk_mul_f32 v[14:15], v[22:23], v[4:5] op_sel_hi:[1,0]
	v_cvt_pk_bf16_f32 v8, v8, v9
	v_cvt_pk_bf16_f32 v9, v10, v11
	v_cvt_pk_bf16_f32 v10, v12, v13
	v_cvt_pk_bf16_f32 v11, v14, v15
	s_nop 1
	v_permlane32_swap_b32 v8, v10
	v_permlane32_swap_b32 v9, v11
	global_store_dwordx4 v[2:3], v[8:11], off offset:192
	s_nop 1
	v_pk_mul_f32 v[8:9], v[24:25], v[4:5] op_sel_hi:[1,0]
	v_pk_mul_f32 v[10:11], v[26:27], v[4:5] op_sel_hi:[1,0]
	v_pk_mul_f32 v[12:13], v[28:29], v[4:5] op_sel_hi:[1,0]
	v_pk_mul_f32 v[14:15], v[30:31], v[4:5] op_sel_hi:[1,0]
	v_cvt_pk_bf16_f32 v8, v8, v9
	v_cvt_pk_bf16_f32 v9, v10, v11
	v_cvt_pk_bf16_f32 v10, v12, v13
	v_cvt_pk_bf16_f32 v11, v14, v15
	s_nop 1
	v_permlane32_swap_b32 v8, v10
	v_permlane32_swap_b32 v9, v11
	global_store_dwordx4 v[2:3], v[8:11], off offset:224
	s_nop 1
	s_branch .LBB0_1285
